# attention C output stores write-through (sc0 sc1) for the cross-XCD handoff to the out-projection GEMM, on top of v91
# speedup vs baseline: 1.0011x; 1.0011x over previous
; __device__ __forceinline__ unsigned cvt_pk_bf16(float lo, float hi) { unsigned r; asm volatile("v_cvt_pk_bf16_f32 %0, %1, %2" : "=v"(r) : "v"(lo), "v"(hi)); return r; }
; template <int NDB> __device__ __forceinline__ void store_o(bf16_t* orow, const f32x16 (&o)[NDB], float inv, int hi, bool valid) {
;     if (!valid) return;
; #pragma unroll
;     for (int db = 0; db < NDB; ++db)
; #pragma unroll
;         for (int g = 0; g < 4; ++g) {
;             u32x2 w; w.x = cvt_pk_bf16(o[db][4 * g] * inv, o[db][4 * g + 1] * inv); w.y = cvt_pk_bf16(o[db][4 * g + 2] * inv, o[db][4 * g + 3] * inv);
;             *(u32x2*)(orow + 32 * db + 8 * g + 4 * hi) = w;
;         }
; }
; __device__ __forceinline__ void attn_c(LAS unsigned char* lds, const Params& P) {
;     ...
;         l_run += __shfl_xor(l_run, 32);
;         store_o<2>(O + qrow * 1024 + h * 64, o, 1.0f / l_run, hi, valid);
.LBB0_2297:
	s_or_b64 exec, exec, s[62:63]
	v_and_b32_e32 v33, 64, v183
	v_xor_b32_e32 v32, 32, v183
	v_add_u32_e32 v33, 64, v33
	v_cmp_lt_i32_e32 vcc, v32, v33
	s_nop 1
	v_cndmask_b32_e32 v32, v183, v32, vcc
	v_lshlrev_b32_e32 v32, 2, v32
	ds_bpermute_b32 v32, v32, v200
	s_and_saveexec_b64 s[0:1], s[60:61]
	s_cbranch_execz .LBB0_2261
	s_waitcnt lgkmcnt(0)
	v_add_f32_e32 v32, v200, v32
	v_div_scale_f32 v33, s[2:3], v32, v32, 1.0
	v_rcp_f32_e32 v34, v33
	v_div_scale_f32 v35, vcc, 1.0, v32, 1.0
	s_lshl_b32 s50, s78, 7
	v_fma_f32 v36, -v33, v34, 1.0
	v_fmac_f32_e32 v34, v36, v34
	v_mul_f32_e32 v36, v35, v34
	v_fma_f32 v37, -v33, v36, v35
	v_fmac_f32_e32 v36, v37, v34
	v_fma_f32 v33, -v33, v36, v35
	v_div_fmas_f32 v33, v33, v34, v36
	v_div_fixup_f32 v34, v33, v32, 1.0
	v_lshlrev_b64 v[32:33], 11, v[150:151]
	v_lshl_add_u64 v[32:33], s[48:49], 0, v[32:33]
	v_mul_f32_e32 v16, v16, v34
	v_mul_f32_e32 v17, v17, v34
	v_lshl_add_u64 v[32:33], v[32:33], 0, s[50:51]
	v_mov_b32_e32 v149, v143
	v_cvt_pk_bf16_f32 v16, v16, v17
	v_mul_f32_e32 v17, v18, v34
	v_lshl_add_u64 v[32:33], v[32:33], 0, v[148:149]
	v_mul_f32_e32 v18, v19, v34
	v_cvt_pk_bf16_f32 v17, v17, v18
	global_store_dwordx2 v[32:33], v[16:17], off sc0 sc1
	v_mul_f32_e32 v16, v20, v34
	v_mul_f32_e32 v17, v21, v34
	v_cvt_pk_bf16_f32 v16, v16, v17
	v_mul_f32_e32 v17, v22, v34
	v_mul_f32_e32 v18, v23, v34
	v_cvt_pk_bf16_f32 v17, v17, v18
	global_store_dwordx2 v[32:33], v[16:17], off offset:16 sc0 sc1
	v_mul_f32_e32 v16, v24, v34
	v_mul_f32_e32 v17, v25, v34
	v_cvt_pk_bf16_f32 v16, v16, v17
	v_mul_f32_e32 v17, v26, v34
	v_mul_f32_e32 v18, v27, v34
	v_cvt_pk_bf16_f32 v17, v17, v18
	global_store_dwordx2 v[32:33], v[16:17], off offset:32 sc0 sc1
	v_mul_f32_e32 v16, v28, v34
	v_mul_f32_e32 v17, v29, v34
	v_cvt_pk_bf16_f32 v16, v16, v17
	v_mul_f32_e32 v17, v30, v34
	v_mul_f32_e32 v0, v0, v34
	v_mul_f32_e32 v1, v1, v34
	v_mul_f32_e32 v18, v31, v34
	v_cvt_pk_bf16_f32 v17, v17, v18
	global_store_dwordx2 v[32:33], v[16:17], off offset:48 sc0 sc1
	v_cvt_pk_bf16_f32 v0, v0, v1
	v_mul_f32_e32 v1, v2, v34
	v_mul_f32_e32 v2, v3, v34
	v_cvt_pk_bf16_f32 v1, v1, v2
	global_store_dwordx2 v[32:33], v[0:1], off offset:64 sc0 sc1
	v_mul_f32_e32 v0, v4, v34
	v_mul_f32_e32 v1, v5, v34
	v_cvt_pk_bf16_f32 v0, v0, v1
	v_mul_f32_e32 v1, v6, v34
	v_mul_f32_e32 v2, v7, v34
	v_cvt_pk_bf16_f32 v1, v1, v2
	global_store_dwordx2 v[32:33], v[0:1], off offset:80 sc0 sc1
	v_mul_f32_e32 v0, v8, v34
	v_mul_f32_e32 v1, v9, v34
	v_cvt_pk_bf16_f32 v0, v0, v1
	v_mul_f32_e32 v1, v10, v34
	v_mul_f32_e32 v2, v11, v34
	v_cvt_pk_bf16_f32 v1, v1, v2
	global_store_dwordx2 v[32:33], v[0:1], off offset:96 sc0 sc1
	v_mul_f32_e32 v0, v12, v34
	v_mul_f32_e32 v1, v13, v34
	v_cvt_pk_bf16_f32 v0, v0, v1
	v_mul_f32_e32 v1, v14, v34
	v_mul_f32_e32 v2, v15, v34
	v_cvt_pk_bf16_f32 v1, v1, v2
	global_store_dwordx2 v[32:33], v[0:1], off offset:112 sc0 sc1
	s_branch .LBB0_2261
